# K loop load windows: LDS-DMA tile loads issued before the window's LDS fragment reads (earlier vector-memory issue)
# speedup vs baseline: 1.0035x; 1.0035x over previous
.LBB0_344:
	s_add_i32 vcc_lo, s50, 2
	s_add_u32 s68, s48, 0x80
	s_addc_u32 s51, s49, 0
	s_add_i32 s70, 0, 0x10000
	s_cmp_eq_u32 s15, s50
	s_cselect_b32 s51, s1, s51
	s_cselect_b32 s50, s0, s68
	v_add_u32_e32 v0, s70, v223
	s_cselect_b32 s69, s53, s57
	s_cselect_b32 s68, s52, s56
	s_add_i32 s71, 0, 0x14000
	v_lshl_add_u64 v[212:213], s[48:49], 0, v[192:193]
	s_add_i32 m0, s67, 0xc000
	global_load_lds_dwordx4 v[212:213], off
	v_lshl_add_u64 v[212:213], s[48:49], 0, v[194:195]
	s_add_i32 m0, s67, 0xe000
	s_nop 0
	global_load_lds_dwordx4 v[212:213], off
	ds_read_b128 v[130:133], v0
	ds_read_b128 v[134:137], v0 offset:1024
	ds_read_b128 v[138:141], v0 offset:2048
	ds_read_b128 v[142:145], v0 offset:3072
	v_add_u32_e32 v0, s71, v223
	ds_read_b128 v[146:149], v0
	ds_read_b128 v[150:153], v0 offset:1024
	ds_read_b128 v[154:157], v0 offset:2048
	ds_read_b128 v[158:161], v0 offset:3072
	ds_read_b128 v[162:165], v226
	ds_read_b128 v[166:169], v226 offset:1024
	ds_read_b128 v[170:173], v226 offset:2048
	ds_read_b128 v[174:177], v226 offset:3072
	ds_read_b128 v[196:199], v226 offset:4096
	ds_read_b128 v[200:203], v226 offset:5120
	ds_read_b128 v[204:207], v226 offset:6144
	ds_read_b128 v[208:211], v226 offset:7168
	s_waitcnt vmcnt(8)
	s_waitcnt lgkmcnt(0)
	s_barrier
	s_setprio 1
	s_waitcnt lgkmcnt(0)
	v_mfma_f32_16x16x32_bf16 v[126:129], v[130:133], v[162:165], v[126:129]
	v_mfma_f32_16x16x32_bf16 v[122:125], v[138:141], v[162:165], v[122:125]
	v_mfma_f32_16x16x32_bf16 v[118:121], v[130:133], v[170:173], v[118:121]
	v_mfma_f32_16x16x32_bf16 v[114:117], v[138:141], v[170:173], v[114:117]
	v_mfma_f32_16x16x32_bf16 v[102:105], v[130:133], v[196:199], v[102:105]
	v_mfma_f32_16x16x32_bf16 v[98:101], v[138:141], v[196:199], v[98:101]
	v_mfma_f32_16x16x32_bf16 v[86:89], v[130:133], v[204:207], v[86:89]
	v_mfma_f32_16x16x32_bf16 v[82:85], v[138:141], v[204:207], v[82:85]
	v_mfma_f32_16x16x32_bf16 v[126:129], v[134:137], v[166:169], v[126:129]
	v_mfma_f32_16x16x32_bf16 v[122:125], v[142:145], v[166:169], v[122:125]
	v_mfma_f32_16x16x32_bf16 v[118:121], v[134:137], v[174:177], v[118:121]
	v_mfma_f32_16x16x32_bf16 v[114:117], v[142:145], v[174:177], v[114:117]
	v_mfma_f32_16x16x32_bf16 v[102:105], v[134:137], v[200:203], v[102:105]
	v_mfma_f32_16x16x32_bf16 v[98:101], v[142:145], v[200:203], v[98:101]
	v_mfma_f32_16x16x32_bf16 v[86:89], v[134:137], v[208:211], v[86:89]
	v_mfma_f32_16x16x32_bf16 v[82:85], v[142:145], v[208:211], v[82:85]
	s_setprio 0
	s_setprio 1
	v_mfma_f32_16x16x32_bf16 v[110:113], v[146:149], v[162:165], v[110:113]
	v_mfma_f32_16x16x32_bf16 v[106:109], v[154:157], v[162:165], v[106:109]
	v_mfma_f32_16x16x32_bf16 v[94:97], v[146:149], v[170:173], v[94:97]
	v_mfma_f32_16x16x32_bf16 v[90:93], v[154:157], v[170:173], v[90:93]
	v_mfma_f32_16x16x32_bf16 v[78:81], v[146:149], v[196:199], v[78:81]
	v_mfma_f32_16x16x32_bf16 v[74:77], v[154:157], v[196:199], v[74:77]
	v_mfma_f32_16x16x32_bf16 v[70:73], v[146:149], v[204:207], v[70:73]
	v_mfma_f32_16x16x32_bf16 v[66:69], v[154:157], v[204:207], v[66:69]
	v_mfma_f32_16x16x32_bf16 v[110:113], v[150:153], v[166:169], v[110:113]
	v_mfma_f32_16x16x32_bf16 v[106:109], v[158:161], v[166:169], v[106:109]
	v_mfma_f32_16x16x32_bf16 v[94:97], v[150:153], v[174:177], v[94:97]
	v_mfma_f32_16x16x32_bf16 v[90:93], v[158:161], v[174:177], v[90:93]
	v_mfma_f32_16x16x32_bf16 v[78:81], v[150:153], v[200:203], v[78:81]
	v_mfma_f32_16x16x32_bf16 v[74:77], v[158:161], v[200:203], v[74:77]
	v_mfma_f32_16x16x32_bf16 v[70:73], v[150:153], v[208:211], v[70:73]
	v_mfma_f32_16x16x32_bf16 v[66:69], v[158:161], v[208:211], v[66:69]
	s_setprio 0
	s_barrier
	s_add_i32 s70, s70, s63
	v_lshl_add_u64 v[212:213], s[68:69], 0, v[186:187]
	s_mov_b32 m0, s70
	global_load_lds_dwordx4 v[212:213], off
	s_add_i32 m0, s70, 0x2000
	v_lshl_add_u64 v[214:215], s[68:69], 0, v[182:183]
	s_add_u32 s68, s68, s90
	s_addc_u32 s69, s69, 0
	s_add_i32 s70, s71, s63
	global_load_lds_dwordx4 v[214:215], off
	v_lshl_add_u64 v[216:217], s[68:69], 0, v[186:187]
	s_mov_b32 m0, s70
	v_lshl_add_u64 v[218:219], s[68:69], 0, v[182:183]
	global_load_lds_dwordx4 v[216:217], off
	s_add_i32 m0, s70, 0x2000
	v_lshl_add_u64 v[232:233], s[50:51], 0, v[184:185]
	global_load_lds_dwordx4 v[218:219], off
	s_mov_b32 m0, s67
	v_lshl_add_u64 v[234:235], s[50:51], 0, v[180:181]
	global_load_lds_dwordx4 v[232:233], off
	s_mov_b32 m0, s33
	s_nop 0
	global_load_lds_dwordx4 v[234:235], off
	ds_read_b128 v[162:165], v226 offset:16384
	ds_read_b128 v[166:169], v226 offset:17408
	ds_read_b128 v[170:173], v226 offset:18432
	ds_read_b128 v[174:177], v226 offset:19456
	ds_read_b128 v[196:199], v226 offset:20480
	ds_read_b128 v[200:203], v226 offset:21504
	ds_read_b128 v[204:207], v226 offset:22528
	ds_read_b128 v[208:211], v226 offset:23552
	s_waitcnt vmcnt(8)
	s_waitcnt lgkmcnt(0)
	s_barrier
	s_setprio 1
	s_waitcnt lgkmcnt(0)
	v_mfma_f32_16x16x32_bf16 v[62:65], v[130:133], v[162:165], v[62:65]
	v_mfma_f32_16x16x32_bf16 v[58:61], v[138:141], v[162:165], v[58:61]
	v_mfma_f32_16x16x32_bf16 v[54:57], v[130:133], v[170:173], v[54:57]
	v_mfma_f32_16x16x32_bf16 v[50:53], v[138:141], v[170:173], v[50:53]
	v_mfma_f32_16x16x32_bf16 v[38:41], v[130:133], v[196:199], v[38:41]
	v_mfma_f32_16x16x32_bf16 v[34:37], v[138:141], v[196:199], v[34:37]
	v_mfma_f32_16x16x32_bf16 v[22:25], v[130:133], v[204:207], v[22:25]
	v_mfma_f32_16x16x32_bf16 v[18:21], v[138:141], v[204:207], v[18:21]
	v_mfma_f32_16x16x32_bf16 v[62:65], v[134:137], v[166:169], v[62:65]
	v_mfma_f32_16x16x32_bf16 v[58:61], v[142:145], v[166:169], v[58:61]
	v_mfma_f32_16x16x32_bf16 v[54:57], v[134:137], v[174:177], v[54:57]
	v_mfma_f32_16x16x32_bf16 v[50:53], v[142:145], v[174:177], v[50:53]
	v_mfma_f32_16x16x32_bf16 v[38:41], v[134:137], v[200:203], v[38:41]
	v_mfma_f32_16x16x32_bf16 v[34:37], v[142:145], v[200:203], v[34:37]
	v_mfma_f32_16x16x32_bf16 v[22:25], v[134:137], v[208:211], v[22:25]
	v_mfma_f32_16x16x32_bf16 v[18:21], v[142:145], v[208:211], v[18:21]
	s_setprio 0
	s_setprio 1
	v_mfma_f32_16x16x32_bf16 v[46:49], v[146:149], v[162:165], v[46:49]
	v_mfma_f32_16x16x32_bf16 v[42:45], v[154:157], v[162:165], v[42:45]
	v_mfma_f32_16x16x32_bf16 v[30:33], v[146:149], v[170:173], v[30:33]
	v_mfma_f32_16x16x32_bf16 v[26:29], v[154:157], v[170:173], v[26:29]
	v_mfma_f32_16x16x32_bf16 v[14:17], v[146:149], v[196:199], v[14:17]
	v_mfma_f32_16x16x32_bf16 v[10:13], v[154:157], v[196:199], v[10:13]
	v_mfma_f32_16x16x32_bf16 v[6:9], v[146:149], v[204:207], v[6:9]
	v_mfma_f32_16x16x32_bf16 v[2:5], v[154:157], v[204:207], v[2:5]
	v_mfma_f32_16x16x32_bf16 v[46:49], v[150:153], v[166:169], v[46:49]
	v_mfma_f32_16x16x32_bf16 v[42:45], v[158:161], v[166:169], v[42:45]
	v_mfma_f32_16x16x32_bf16 v[30:33], v[150:153], v[174:177], v[30:33]
	v_mfma_f32_16x16x32_bf16 v[26:29], v[158:161], v[174:177], v[26:29]
	v_mfma_f32_16x16x32_bf16 v[14:17], v[150:153], v[200:203], v[14:17]
	v_mfma_f32_16x16x32_bf16 v[10:13], v[158:161], v[200:203], v[10:13]
	v_mfma_f32_16x16x32_bf16 v[6:9], v[150:153], v[208:211], v[6:9]
	v_mfma_f32_16x16x32_bf16 v[2:5], v[158:161], v[208:211], v[2:5]
	s_setprio 0
	s_barrier
	s_add_i32 s68, 0, 0x18000
	v_add_u32_e32 v0, s68, v223
	s_add_i32 s69, 0, 0x1c000
	s_add_u32 s50, s50, s90
	s_addc_u32 s51, s51, 0
	s_mov_b32 m0, s65
	v_lshl_add_u64 v[236:237], s[50:51], 0, v[184:185]
	global_load_lds_dwordx4 v[236:237], off
	v_lshl_add_u64 v[236:237], s[50:51], 0, v[180:181]
	s_mov_b32 m0, s22
	s_nop 0
	global_load_lds_dwordx4 v[236:237], off
	ds_read_b128 v[130:133], v0
	ds_read_b128 v[134:137], v0 offset:1024
	ds_read_b128 v[138:141], v0 offset:2048
	ds_read_b128 v[142:145], v0 offset:3072
	v_add_u32_e32 v0, s69, v223
	ds_read_b128 v[146:149], v0
	ds_read_b128 v[150:153], v0 offset:1024
	ds_read_b128 v[154:157], v0 offset:2048
	ds_read_b128 v[158:161], v0 offset:3072
	ds_read_b128 v[162:165], v226 offset:32768
	ds_read_b128 v[166:169], v226 offset:33792
	ds_read_b128 v[170:173], v226 offset:34816
	ds_read_b128 v[174:177], v226 offset:35840
	ds_read_b128 v[196:199], v226 offset:36864
	ds_read_b128 v[200:203], v226 offset:37888
	ds_read_b128 v[204:207], v226 offset:38912
	ds_read_b128 v[208:211], v226 offset:39936
	s_waitcnt vmcnt(8)
	s_waitcnt lgkmcnt(0)
	s_barrier
	s_setprio 1
	s_waitcnt lgkmcnt(0)
	v_mfma_f32_16x16x32_bf16 v[126:129], v[130:133], v[162:165], v[126:129]
	v_mfma_f32_16x16x32_bf16 v[122:125], v[138:141], v[162:165], v[122:125]
	v_mfma_f32_16x16x32_bf16 v[118:121], v[130:133], v[170:173], v[118:121]
	v_mfma_f32_16x16x32_bf16 v[114:117], v[138:141], v[170:173], v[114:117]
	v_mfma_f32_16x16x32_bf16 v[102:105], v[130:133], v[196:199], v[102:105]
	v_mfma_f32_16x16x32_bf16 v[98:101], v[138:141], v[196:199], v[98:101]
	v_mfma_f32_16x16x32_bf16 v[86:89], v[130:133], v[204:207], v[86:89]
	v_mfma_f32_16x16x32_bf16 v[82:85], v[138:141], v[204:207], v[82:85]
	v_mfma_f32_16x16x32_bf16 v[126:129], v[134:137], v[166:169], v[126:129]
	v_mfma_f32_16x16x32_bf16 v[122:125], v[142:145], v[166:169], v[122:125]
	v_mfma_f32_16x16x32_bf16 v[118:121], v[134:137], v[174:177], v[118:121]
	v_mfma_f32_16x16x32_bf16 v[114:117], v[142:145], v[174:177], v[114:117]
	v_mfma_f32_16x16x32_bf16 v[102:105], v[134:137], v[200:203], v[102:105]
	v_mfma_f32_16x16x32_bf16 v[98:101], v[142:145], v[200:203], v[98:101]
	v_mfma_f32_16x16x32_bf16 v[86:89], v[134:137], v[208:211], v[86:89]
	v_mfma_f32_16x16x32_bf16 v[82:85], v[142:145], v[208:211], v[82:85]
	s_setprio 0
	s_setprio 1
	v_mfma_f32_16x16x32_bf16 v[110:113], v[146:149], v[162:165], v[110:113]
	v_mfma_f32_16x16x32_bf16 v[106:109], v[154:157], v[162:165], v[106:109]
	v_mfma_f32_16x16x32_bf16 v[94:97], v[146:149], v[170:173], v[94:97]
	v_mfma_f32_16x16x32_bf16 v[90:93], v[154:157], v[170:173], v[90:93]
	v_mfma_f32_16x16x32_bf16 v[78:81], v[146:149], v[196:199], v[78:81]
	v_mfma_f32_16x16x32_bf16 v[74:77], v[154:157], v[196:199], v[74:77]
	v_mfma_f32_16x16x32_bf16 v[70:73], v[146:149], v[204:207], v[70:73]
	v_mfma_f32_16x16x32_bf16 v[66:69], v[154:157], v[204:207], v[66:69]
	v_mfma_f32_16x16x32_bf16 v[110:113], v[150:153], v[166:169], v[110:113]
	v_mfma_f32_16x16x32_bf16 v[106:109], v[158:161], v[166:169], v[106:109]
	v_mfma_f32_16x16x32_bf16 v[94:97], v[150:153], v[174:177], v[94:97]
	v_mfma_f32_16x16x32_bf16 v[90:93], v[158:161], v[174:177], v[90:93]
	v_mfma_f32_16x16x32_bf16 v[78:81], v[150:153], v[200:203], v[78:81]
	v_mfma_f32_16x16x32_bf16 v[74:77], v[158:161], v[200:203], v[74:77]
	v_mfma_f32_16x16x32_bf16 v[70:73], v[150:153], v[208:211], v[70:73]
	v_mfma_f32_16x16x32_bf16 v[66:69], v[158:161], v[208:211], v[66:69]
	s_setprio 0
	s_barrier
	s_add_i32 s50, s68, s63
	v_lshl_add_u64 v[212:213], v[212:213], 0, s[94:95]
	s_mov_b32 m0, s50
	global_load_lds_dwordx4 v[212:213], off
	v_lshl_add_u64 v[212:213], v[214:215], 0, s[94:95]
	s_add_i32 m0, s50, 0x2000
	s_add_i32 s50, s69, s63
	global_load_lds_dwordx4 v[212:213], off
	v_lshl_add_u64 v[212:213], v[216:217], 0, s[94:95]
	s_mov_b32 m0, s50
	s_nop 0
	global_load_lds_dwordx4 v[212:213], off
	v_lshl_add_u64 v[212:213], v[218:219], 0, s[94:95]
	s_add_i32 m0, s50, 0x2000
	s_nop 0
	global_load_lds_dwordx4 v[212:213], off
	v_lshl_add_u64 v[212:213], v[232:233], 0, s[94:95]
	s_mov_b32 m0, s87
	s_nop 0
	global_load_lds_dwordx4 v[212:213], off
	v_lshl_add_u64 v[212:213], v[234:235], 0, s[94:95]
	s_mov_b32 m0, s2
	s_nop 0
	global_load_lds_dwordx4 v[212:213], off
	ds_read_b128 v[162:165], v226 offset:49152
	ds_read_b128 v[166:169], v226 offset:50176
	ds_read_b128 v[170:173], v226 offset:51200
	ds_read_b128 v[174:177], v226 offset:52224
	ds_read_b128 v[196:199], v226 offset:53248
	ds_read_b128 v[200:203], v226 offset:54272
	ds_read_b128 v[204:207], v226 offset:55296
	ds_read_b128 v[208:211], v226 offset:56320
	s_waitcnt vmcnt(8)
	s_waitcnt lgkmcnt(0)
	s_barrier
	s_setprio 1
	s_waitcnt lgkmcnt(0)
	v_mfma_f32_16x16x32_bf16 v[62:65], v[130:133], v[162:165], v[62:65]
	v_mfma_f32_16x16x32_bf16 v[58:61], v[138:141], v[162:165], v[58:61]
	v_mfma_f32_16x16x32_bf16 v[54:57], v[130:133], v[170:173], v[54:57]
	v_mfma_f32_16x16x32_bf16 v[50:53], v[138:141], v[170:173], v[50:53]
	v_mfma_f32_16x16x32_bf16 v[38:41], v[130:133], v[196:199], v[38:41]
	v_mfma_f32_16x16x32_bf16 v[34:37], v[138:141], v[196:199], v[34:37]
	v_mfma_f32_16x16x32_bf16 v[22:25], v[130:133], v[204:207], v[22:25]
	v_mfma_f32_16x16x32_bf16 v[18:21], v[138:141], v[204:207], v[18:21]
	v_mfma_f32_16x16x32_bf16 v[62:65], v[134:137], v[166:169], v[62:65]
	v_mfma_f32_16x16x32_bf16 v[58:61], v[142:145], v[166:169], v[58:61]
	v_mfma_f32_16x16x32_bf16 v[54:57], v[134:137], v[174:177], v[54:57]
	v_mfma_f32_16x16x32_bf16 v[50:53], v[142:145], v[174:177], v[50:53]
	v_mfma_f32_16x16x32_bf16 v[38:41], v[134:137], v[200:203], v[38:41]
	v_mfma_f32_16x16x32_bf16 v[34:37], v[142:145], v[200:203], v[34:37]
	v_mfma_f32_16x16x32_bf16 v[22:25], v[134:137], v[208:211], v[22:25]
	v_mfma_f32_16x16x32_bf16 v[18:21], v[142:145], v[208:211], v[18:21]
	s_setprio 0
	s_setprio 1
	v_mfma_f32_16x16x32_bf16 v[46:49], v[146:149], v[162:165], v[46:49]
	v_mfma_f32_16x16x32_bf16 v[42:45], v[154:157], v[162:165], v[42:45]
	v_mfma_f32_16x16x32_bf16 v[30:33], v[146:149], v[170:173], v[30:33]
	v_mfma_f32_16x16x32_bf16 v[26:29], v[154:157], v[170:173], v[26:29]
	v_mfma_f32_16x16x32_bf16 v[14:17], v[146:149], v[196:199], v[14:17]
	v_mfma_f32_16x16x32_bf16 v[10:13], v[154:157], v[196:199], v[10:13]
	v_mfma_f32_16x16x32_bf16 v[6:9], v[146:149], v[204:207], v[6:9]
	v_mfma_f32_16x16x32_bf16 v[2:5], v[154:157], v[204:207], v[2:5]
	v_mfma_f32_16x16x32_bf16 v[46:49], v[150:153], v[166:169], v[46:49]
	v_mfma_f32_16x16x32_bf16 v[42:45], v[158:161], v[166:169], v[42:45]
	v_mfma_f32_16x16x32_bf16 v[30:33], v[150:153], v[174:177], v[30:33]
	v_mfma_f32_16x16x32_bf16 v[26:29], v[158:161], v[174:177], v[26:29]
	v_mfma_f32_16x16x32_bf16 v[14:17], v[150:153], v[200:203], v[14:17]
	v_mfma_f32_16x16x32_bf16 v[10:13], v[158:161], v[200:203], v[10:13]
	v_mfma_f32_16x16x32_bf16 v[6:9], v[150:153], v[208:211], v[6:9]
	v_mfma_f32_16x16x32_bf16 v[2:5], v[158:161], v[208:211], v[2:5]
	s_setprio 0
	s_barrier
	s_add_u32 s48, s48, 0x100
	s_addc_u32 s49, s49, 0
	s_add_u32 s56, s56, 0x100
	s_addc_u32 s57, s57, 0
	s_cmp_ge_i32 vcc_lo, s55
	s_mov_b32 s50, vcc_lo
	s_cbranch_scc0 .LBB0_344
